# prompt attention PV: V-fragment ds_reads issued two MFMAs ahead into fresh buffers, counted lgkmcnt instead of lgkmcnt(0) per MFMA
# speedup vs baseline: 1.0095x; 1.0095x over previous
.LBB0_812:
	s_or_b64 exec, exec, s[52:53]
	s_ashr_i32 s49, s48, 31
	s_lshl_b64 s[48:49], s[48:49], 2
	s_add_u32 s48, s3, s48
	s_addc_u32 s49, s82, s49
	s_waitcnt lgkmcnt(0)
	s_barrier
	global_load_dword v149, v195, s[48:49]
	ds_read_b128 v[2:5], v142
	ds_read_b128 v[6:9], v142 offset:32
	s_waitcnt lgkmcnt(1)
	v_mfma_f32_32x32x16_bf16 v[66:81], v[2:5], v[34:37], 0
	ds_read_b128 v[2:5], v142 offset:64
	v_lshl_add_u64 v[126:127], s[50:51], 1, v[118:119]
	s_and_b64 s[48:49], vcc, s[12:13]
	s_and_b64 s[50:51], vcc, s[14:15]
	s_and_b64 s[52:53], vcc, s[16:17]
	s_and_b64 s[54:55], vcc, s[18:19]
	s_and_b64 s[56:57], vcc, s[20:21]
	s_waitcnt lgkmcnt(1)
	v_mfma_f32_32x32x16_bf16 v[66:81], v[6:9], v[106:109], v[66:81]
	s_and_b64 s[58:59], vcc, s[22:23]
	s_and_b64 s[60:61], vcc, s[24:25]
	s_and_b64 s[62:63], vcc, s[26:27]
	s_and_b64 s[64:65], vcc, s[28:29]
	s_and_b64 s[66:67], vcc, s[30:31]
	s_and_b64 s[68:69], vcc, s[34:35]
	s_and_b64 s[70:71], vcc, s[36:37]
	s_waitcnt lgkmcnt(0)
	v_mfma_f32_32x32x16_bf16 v[66:81], v[2:5], v[102:105], v[66:81]
	ds_read_b128 v[2:5], v142 offset:96
	s_and_b64 s[72:73], vcc, s[38:39]
	s_and_b64 s[74:75], vcc, s[42:43]
	s_and_b64 s[76:77], vcc, s[44:45]
	s_and_b64 s[78:79], vcc, s[0:1]
	s_or_b32 s80, s80, s96
	s_cmp_eq_u32 s80, 0
	s_waitcnt lgkmcnt(0)
	v_mfma_f32_32x32x16_bf16 v[66:81], v[2:5], v[98:101], v[66:81]
	ds_read_b128 v[2:5], v143
	ds_read_b128 v[6:9], v143 offset:32
	s_cselect_b64 s[80:81], -1, 0
	s_mov_b32 s94, 0x3fb8aa3b
	v_or_b32_e32 v152, s97, v150
	s_add_i32 s2, s2, s86
	s_cmpk_lt_i32 s2, 0x200
	s_nop 4
	v_cndmask_b32_e64 v67, v245, v67, s[50:51]
	s_waitcnt lgkmcnt(1)
	v_mfma_f32_32x32x16_bf16 v[50:65], v[2:5], v[34:37], 0
	ds_read_b128 v[2:5], v143 offset:64
	v_cndmask_b32_e64 v68, v245, v68, s[52:53]
	v_cndmask_b32_e64 v69, v245, v69, s[54:55]
	v_cndmask_b32_e64 v70, v245, v70, s[56:57]
	v_cndmask_b32_e64 v71, v245, v71, s[58:59]
	v_cndmask_b32_e64 v72, v245, v72, s[60:61]
	v_cndmask_b32_e64 v75, v245, v75, s[66:67]
	s_waitcnt lgkmcnt(1)
	v_mfma_f32_32x32x16_bf16 v[50:65], v[6:9], v[106:109], v[50:65]
	v_cndmask_b32_e64 v78, v245, v78, s[72:73]
	v_cndmask_b32_e64 v79, v245, v79, s[74:75]
	v_cndmask_b32_e64 v80, v245, v80, s[76:77]
	v_cndmask_b32_e64 v81, v245, v81, s[78:79]
	s_waitcnt vmcnt(0)
	v_mul_f32_e32 v151, 0x3fb8aa3b, v149
	s_waitcnt lgkmcnt(0)
	v_mfma_f32_32x32x16_bf16 v[50:65], v[2:5], v[102:105], v[50:65]
	ds_read_b128 v[2:5], v143 offset:96
	s_waitcnt lgkmcnt(0)
	v_mfma_f32_32x32x16_bf16 v[50:65], v[2:5], v[98:101], v[50:65]
	ds_read_b128 v[2:5], v144
	ds_read_b128 v[6:9], v144 offset:32
	s_waitcnt lgkmcnt(1)
	v_mfma_f32_32x32x16_bf16 v[18:33], v[2:5], v[34:37], 0
	ds_read_b128 v[2:5], v144 offset:64
	s_nop 6
	v_cndmask_b32_e32 v50, v245, v50, vcc
	v_cndmask_b32_e32 v54, v245, v54, vcc
	v_cndmask_b32_e32 v59, v245, v59, vcc
	v_cndmask_b32_e32 v60, v245, v60, vcc
	v_cndmask_b32_e32 v153, v245, v61, vcc
	v_cndmask_b32_e32 v63, v245, v63, vcc
	s_waitcnt lgkmcnt(1)
	v_mfma_f32_32x32x16_bf16 v[18:33], v[6:9], v[106:109], v[18:33]
	v_cndmask_b32_e32 v65, v245, v65, vcc
	s_waitcnt lgkmcnt(0)
	v_mfma_f32_32x32x16_bf16 v[18:33], v[2:5], v[102:105], v[18:33]
	ds_read_b128 v[2:5], v144 offset:96
	s_waitcnt lgkmcnt(0)
	v_mfma_f32_32x32x16_bf16 v[18:33], v[2:5], v[98:101], v[18:33]
	ds_read_b128 v[2:5], v145
	ds_read_b128 v[38:41], v145 offset:32
	s_waitcnt lgkmcnt(1)
	v_mfma_f32_32x32x16_bf16 v[2:17], v[2:5], v[34:37], 0
	s_nop 7
	v_cndmask_b32_e64 v158, v20, v245, s[80:81]
	v_cndmask_b32_e64 v159, v21, v245, s[80:81]
	v_cndmask_b32_e64 v160, v22, v245, s[80:81]
	v_cndmask_b32_e64 v161, v23, v245, s[80:81]
	v_cndmask_b32_e64 v162, v24, v245, s[80:81]
	v_cndmask_b32_e64 v163, v25, v245, s[80:81]
	v_cndmask_b32_e64 v164, v26, v245, s[80:81]
	s_waitcnt lgkmcnt(0)
	v_mfma_f32_32x32x16_bf16 v[2:17], v[38:41], v[106:109], v[2:17]
	ds_read_b128 v[38:41], v145 offset:64
	v_cndmask_b32_e64 v165, v27, v245, s[80:81]
	v_cndmask_b32_e64 v166, v28, v245, s[80:81]
	v_cndmask_b32_e64 v167, v29, v245, s[80:81]
	v_cndmask_b32_e64 v168, v30, v245, s[80:81]
	s_waitcnt lgkmcnt(0)
	v_mfma_f32_32x32x16_bf16 v[2:17], v[38:41], v[102:105], v[2:17]
	ds_read_b128 v[38:41], v145 offset:96
	s_waitcnt lgkmcnt(0)
	v_mfma_f32_32x32x16_bf16 v[2:17], v[38:41], v[98:101], v[2:17]
	ds_read_b128 v[38:41], v146
	ds_read_b128 v[154:157], v146 offset:32
	s_waitcnt lgkmcnt(1)
	v_mfma_f32_32x32x16_bf16 v[34:49], v[38:41], v[34:37], 0
	s_nop 7
	v_cndmask_b32_e64 v61, v5, v245, s[80:81]
	v_cndmask_b32_e64 v30, v14, v245, s[80:81]
	v_cndmask_b32_e64 v29, v15, v245, s[80:81]
	v_cndmask_b32_e64 v28, v16, v245, s[80:81]
	v_cndmask_b32_e64 v27, v17, v245, s[80:81]
	s_waitcnt lgkmcnt(0)
	v_mfma_f32_32x32x16_bf16 v[34:49], v[154:157], v[106:109], v[34:49]
	ds_read_b128 v[106:109], v146 offset:64
	v_cndmask_b32_e32 v154, v245, v62, vcc
	v_cndmask_b32_e32 v155, v245, v64, vcc
	v_cndmask_b32_e64 v156, v18, v245, s[80:81]
	v_cndmask_b32_e64 v157, v19, v245, s[80:81]
	v_cndmask_b32_e64 v64, v4, v245, s[80:81]
	s_waitcnt lgkmcnt(0)
	v_mfma_f32_32x32x16_bf16 v[34:49], v[106:109], v[102:105], v[34:49]
	ds_read_b128 v[102:105], v146 offset:96
	v_cndmask_b32_e32 v106, v245, v55, vcc
	v_cndmask_b32_e32 v107, v245, v56, vcc
	v_cndmask_b32_e32 v108, v245, v57, vcc
	v_cndmask_b32_e32 v109, v245, v58, vcc
	v_cndmask_b32_e64 v58, v6, v245, s[80:81]
	v_cndmask_b32_e64 v57, v7, v245, s[80:81]
	s_waitcnt lgkmcnt(0)
	v_mfma_f32_32x32x16_bf16 v[34:49], v[102:105], v[98:101], v[34:49]
	v_cndmask_b32_e64 v98, v245, v66, s[48:49]
	v_max3_f32 v66, v151, v98, v67
	v_max3_f32 v66, v66, v68, v69
	v_max3_f32 v66, v66, v70, v71
	v_cndmask_b32_e64 v99, v245, v73, s[62:63]
	v_max3_f32 v66, v66, v72, v99
	v_cndmask_b32_e64 v100, v245, v74, s[64:65]
	v_max3_f32 v66, v66, v100, v75
	v_cndmask_b32_e64 v101, v245, v76, s[68:69]
	v_cndmask_b32_e64 v102, v245, v77, s[70:71]
	v_max3_f32 v66, v66, v101, v102
	v_max3_f32 v66, v66, v78, v79
	v_max3_f32 v66, v66, v80, v81
	v_cndmask_b32_e32 v103, v245, v51, vcc
	v_max3_f32 v51, v66, v50, v103
	v_cndmask_b32_e32 v104, v245, v52, vcc
	v_cndmask_b32_e32 v105, v245, v53, vcc
	v_max3_f32 v51, v51, v104, v105
	v_max3_f32 v51, v51, v54, v106
	v_max3_f32 v51, v51, v107, v108
	v_max3_f32 v51, v51, v109, v59
	v_max3_f32 v51, v51, v60, v153
	v_max3_f32 v51, v51, v154, v63
	v_max3_f32 v51, v51, v155, v65
	v_max3_f32 v18, v51, v156, v157
	v_max3_f32 v18, v18, v158, v159
	v_max3_f32 v18, v18, v160, v161
	v_max3_f32 v18, v18, v162, v163
	v_max3_f32 v18, v18, v164, v165
	v_max3_f32 v18, v18, v166, v167
	v_cndmask_b32_e64 v77, v31, v245, s[80:81]
	v_max3_f32 v18, v18, v168, v77
	v_cndmask_b32_e64 v76, v32, v245, s[80:81]
	v_cndmask_b32_e64 v74, v33, v245, s[80:81]
	v_max3_f32 v18, v18, v76, v74
	v_cndmask_b32_e64 v73, v2, v245, s[80:81]
	v_cndmask_b32_e64 v66, v3, v245, s[80:81]
	v_max3_f32 v2, v18, v73, v66
	v_max3_f32 v2, v2, v64, v61
	v_max3_f32 v2, v2, v58, v57
	v_cndmask_b32_e64 v55, v8, v245, s[80:81]
	v_cndmask_b32_e64 v53, v9, v245, s[80:81]
	v_max3_f32 v2, v2, v55, v53
	v_cndmask_b32_e64 v52, v10, v245, s[80:81]
	v_cndmask_b32_e64 v33, v11, v245, s[80:81]
	v_max3_f32 v2, v2, v52, v33
	v_cndmask_b32_e64 v32, v12, v245, s[80:81]
	v_cndmask_b32_e64 v31, v13, v245, s[80:81]
	v_max3_f32 v2, v2, v32, v31
	v_max3_f32 v2, v2, v30, v29
	v_max3_f32 v2, v2, v28, v27
	v_cndmask_b32_e64 v26, v34, v245, s[12:13]
	v_cndmask_b32_e64 v25, v245, v35, s[46:47]
	v_max3_f32 v2, v2, v26, v25
	v_cndmask_b32_e64 v24, v36, v245, s[16:17]
	v_cndmask_b32_e64 v23, v37, v245, s[18:19]
	v_max3_f32 v2, v2, v24, v23
	v_cndmask_b32_e64 v22, v38, v245, s[20:21]
	v_cndmask_b32_e64 v21, v39, v245, s[22:23]
	v_max3_f32 v2, v2, v22, v21
	v_cndmask_b32_e64 v20, v40, v245, s[24:25]
	v_cndmask_b32_e64 v19, v41, v245, s[26:27]
	v_max3_f32 v2, v2, v20, v19
	v_cndmask_b32_e64 v18, v42, v245, s[28:29]
	v_cndmask_b32_e64 v17, v43, v245, s[30:31]
	v_max3_f32 v2, v2, v18, v17
	v_cndmask_b32_e64 v16, v44, v245, s[34:35]
	v_cndmask_b32_e64 v15, v45, v245, s[36:37]
	v_max3_f32 v2, v2, v16, v15
	v_cndmask_b32_e64 v14, v46, v245, s[38:39]
	v_cndmask_b32_e64 v13, v47, v245, s[42:43]
	v_max3_f32 v2, v2, v14, v13
	v_cndmask_b32_e64 v12, v48, v245, s[44:45]
	v_cndmask_b32_e64 v11, v49, v245, s[0:1]
	v_max3_f32 v2, v2, v12, v11
	ds_bpermute_b32 v3, v129, v2
	s_waitcnt lgkmcnt(0)
	v_max_f32_e32 v3, v3, v3
	v_max_f32_e32 v10, v2, v3
	v_sub_f32_e32 v2, v98, v10
	v_exp_f32_e32 v2, v2
	v_sub_f32_e32 v3, v67, v10
	v_exp_f32_e32 v3, v3
	v_sub_f32_e32 v35, v100, v10
	v_add_f32_e32 v4, 0, v2
	v_exp_f32_e32 v35, v35
	v_add_f32_e32 v5, v3, v4
	v_sub_f32_e32 v4, v68, v10
	v_exp_f32_e32 v4, v4
	v_sub_f32_e32 v36, v75, v10
	v_exp_f32_e32 v36, v36
	v_sub_f32_e32 v37, v101, v10
	v_add_f32_e32 v6, v4, v5
	v_sub_f32_e32 v5, v69, v10
	v_exp_f32_e32 v5, v5
	v_exp_f32_e32 v38, v37
	v_sub_f32_e32 v37, v102, v10
	v_exp_f32_e32 v39, v37
	v_add_f32_e32 v7, v5, v6
	v_sub_f32_e32 v6, v70, v10
	v_exp_f32_e32 v6, v6
	v_sub_f32_e32 v37, v78, v10
	v_exp_f32_e32 v40, v37
	v_sub_f32_e32 v37, v79, v10
	v_add_f32_e32 v8, v6, v7
	v_sub_f32_e32 v7, v71, v10
	v_exp_f32_e32 v7, v7
	v_exp_f32_e32 v45, v37
	v_sub_f32_e32 v37, v80, v10
	v_exp_f32_e32 v48, v37
	v_add_f32_e32 v9, v7, v8
	v_sub_f32_e32 v8, v72, v10
	v_exp_f32_e32 v8, v8
	v_sub_f32_e32 v37, v81, v10
	v_exp_f32_e32 v51, v37
	v_sub_f32_e32 v37, v50, v10
	v_add_f32_e32 v34, v8, v9
	v_sub_f32_e32 v9, v99, v10
	v_exp_f32_e32 v9, v9
	v_exp_f32_e32 v37, v37
	v_sub_f32_e32 v41, v103, v10
	v_exp_f32_e32 v41, v41
	v_add_f32_e32 v34, v9, v34
	v_add_f32_e32 v34, v35, v34
	v_add_f32_e32 v34, v36, v34
	v_add_f32_e32 v34, v38, v34
	v_add_f32_e32 v34, v39, v34
	v_add_f32_e32 v34, v40, v34
	v_add_f32_e32 v34, v45, v34
	v_sub_f32_e32 v42, v104, v10
	v_add_f32_e32 v34, v48, v34
	v_exp_f32_e32 v43, v42
	v_sub_f32_e32 v42, v105, v10
	v_add_f32_e32 v34, v51, v34
	v_exp_f32_e32 v44, v42
	v_sub_f32_e32 v42, v54, v10
	v_add_f32_e32 v34, v37, v34
	v_exp_f32_e32 v47, v42
	v_sub_f32_e32 v42, v106, v10
	v_add_f32_e32 v34, v41, v34
	v_exp_f32_e32 v56, v42
	v_sub_f32_e32 v42, v107, v10
	v_add_f32_e32 v34, v43, v34
	v_exp_f32_e32 v62, v42
	v_sub_f32_e32 v42, v108, v10
	v_add_f32_e32 v34, v44, v34
	v_exp_f32_e32 v67, v42
	v_sub_f32_e32 v42, v109, v10
	v_add_f32_e32 v34, v47, v34
	v_exp_f32_e32 v42, v42
	v_sub_f32_e32 v46, v59, v10
	v_add_f32_e32 v34, v56, v34
	v_exp_f32_e32 v46, v46
	v_sub_f32_e32 v49, v60, v10
	v_add_f32_e32 v34, v62, v34
	v_exp_f32_e32 v50, v49
	v_sub_f32_e32 v49, v153, v10
	v_add_f32_e32 v34, v67, v34
	v_exp_f32_e32 v54, v49
	v_sub_f32_e32 v49, v154, v10
	v_add_f32_e32 v34, v42, v34
	v_exp_f32_e32 v59, v49
	v_sub_f32_e32 v49, v63, v10
	v_add_f32_e32 v34, v46, v34
	v_exp_f32_e32 v69, v49
	v_sub_f32_e32 v49, v155, v10
	v_add_f32_e32 v34, v50, v34
	v_exp_f32_e32 v72, v49
	v_sub_f32_e32 v49, v65, v10
	v_add_f32_e32 v34, v54, v34
	v_exp_f32_e32 v78, v49
	v_sub_f32_e32 v49, v156, v10
	v_add_f32_e32 v34, v59, v34
	v_exp_f32_e32 v49, v49
	v_sub_f32_e32 v60, v157, v10
	v_add_f32_e32 v34, v69, v34
	v_exp_f32_e32 v60, v60
	v_sub_f32_e32 v63, v158, v10
	v_add_f32_e32 v34, v72, v34
	v_exp_f32_e32 v65, v63
	v_sub_f32_e32 v63, v159, v10
	v_add_f32_e32 v34, v78, v34
	v_exp_f32_e32 v68, v63
	v_sub_f32_e32 v63, v160, v10
	v_add_f32_e32 v34, v49, v34
	v_exp_f32_e32 v71, v63
	v_sub_f32_e32 v63, v161, v10
	v_add_f32_e32 v34, v60, v34
	v_exp_f32_e32 v98, v63
	v_sub_f32_e32 v63, v162, v10
	v_add_f32_e32 v34, v65, v34
	v_exp_f32_e32 v103, v63
	v_sub_f32_e32 v63, v163, v10
	v_add_f32_e32 v34, v68, v34
	v_exp_f32_e32 v104, v63
	v_sub_f32_e32 v63, v164, v10
	v_add_f32_e32 v34, v71, v34
	v_exp_f32_e32 v63, v63
	v_sub_f32_e32 v70, v165, v10
	v_add_f32_e32 v34, v98, v34
	v_exp_f32_e32 v70, v70
	v_sub_f32_e32 v75, v166, v10
	v_add_f32_e32 v34, v103, v34
	v_exp_f32_e32 v75, v75
	v_sub_f32_e32 v79, v167, v10
	v_add_f32_e32 v34, v104, v34
	v_exp_f32_e32 v80, v79
	v_sub_f32_e32 v79, v168, v10
	v_add_f32_e32 v34, v63, v34
	v_exp_f32_e32 v101, v79
	v_sub_f32_e32 v77, v77, v10
	v_add_f32_e32 v34, v70, v34
	v_exp_f32_e32 v155, v77
	v_sub_f32_e32 v76, v76, v10
	v_add_f32_e32 v34, v75, v34
	v_exp_f32_e32 v159, v76
	v_sub_f32_e32 v74, v74, v10
	v_add_f32_e32 v34, v80, v34
	v_exp_f32_e32 v163, v74
	v_sub_f32_e32 v73, v73, v10
	v_add_f32_e32 v34, v101, v34
	v_exp_f32_e32 v74, v73
	v_sub_f32_e32 v66, v66, v10
	v_add_f32_e32 v34, v155, v34
	v_exp_f32_e32 v102, v66
	v_sub_f32_e32 v64, v64, v10
	v_add_f32_e32 v34, v159, v34
	v_exp_f32_e32 v153, v64
	v_sub_f32_e32 v61, v61, v10
	v_add_f32_e32 v34, v163, v34
	v_exp_f32_e32 v154, v61
	v_sub_f32_e32 v58, v58, v10
	v_add_f32_e32 v34, v74, v34
	v_exp_f32_e32 v157, v58
	v_sub_f32_e32 v57, v57, v10
	v_add_f32_e32 v34, v102, v34
	v_exp_f32_e32 v166, v57
	v_sub_f32_e32 v55, v55, v10
	v_add_f32_e32 v34, v153, v34
	v_exp_f32_e32 v167, v55
	v_sub_f32_e32 v53, v53, v10
	v_add_f32_e32 v34, v154, v34
	v_exp_f32_e32 v168, v53
	v_sub_f32_e32 v52, v52, v10
	v_add_f32_e32 v34, v157, v34
	v_exp_f32_e32 v109, v52
	v_sub_f32_e32 v33, v33, v10
	v_add_f32_e32 v34, v166, v34
	v_exp_f32_e32 v156, v33
	v_sub_f32_e32 v32, v32, v10
	v_add_f32_e32 v34, v167, v34
	v_exp_f32_e32 v158, v32
	v_sub_f32_e32 v31, v31, v10
	v_add_f32_e32 v34, v168, v34
	v_exp_f32_e32 v160, v31
	v_sub_f32_e32 v30, v30, v10
	v_add_f32_e32 v34, v109, v34
	v_exp_f32_e32 v161, v30
	v_sub_f32_e32 v29, v29, v10
	v_add_f32_e32 v33, v156, v34
	v_exp_f32_e32 v162, v29
	v_sub_f32_e32 v28, v28, v10
	v_add_f32_e32 v32, v158, v33
	v_exp_f32_e32 v164, v28
	v_sub_f32_e32 v27, v27, v10
	v_add_f32_e32 v31, v160, v32
	v_exp_f32_e32 v165, v27
	v_sub_f32_e32 v26, v26, v10
	v_add_f32_e32 v30, v161, v31
	v_exp_f32_e32 v73, v26
	v_sub_f32_e32 v25, v25, v10
	v_add_f32_e32 v29, v162, v30
	v_exp_f32_e32 v76, v25
	v_sub_f32_e32 v24, v24, v10
	v_add_f32_e32 v28, v164, v29
	v_exp_f32_e32 v77, v24
	v_sub_f32_e32 v23, v23, v10
	v_add_f32_e32 v27, v165, v28
	v_exp_f32_e32 v79, v23
	v_sub_f32_e32 v22, v22, v10
	v_add_f32_e32 v26, v73, v27
	v_exp_f32_e32 v81, v22
	v_sub_f32_e32 v21, v21, v10
	v_add_f32_e32 v25, v76, v26
	v_exp_f32_e32 v99, v21
	v_sub_f32_e32 v20, v20, v10
	v_add_f32_e32 v24, v77, v25
	v_exp_f32_e32 v100, v20
	v_sub_f32_e32 v19, v19, v10
	v_add_u32_e32 v105, v130, v131
	v_add_f32_e32 v23, v79, v24
	v_exp_f32_e32 v108, v19
	v_sub_f32_e32 v18, v18, v10
	v_cvt_pk_bf16_f32 v2, v2, v3
	v_cvt_pk_bf16_f32 v3, v4, v5
	v_cvt_pk_bf16_f32 v4, v6, v7
	v_cvt_pk_bf16_f32 v5, v8, v9
	ds_read_b128 v[6:9], v105 offset:36864
	v_add_f32_e32 v22, v81, v23
	v_exp_f32_e32 v52, v18
	v_sub_f32_e32 v17, v17, v10
	v_add_f32_e32 v21, v99, v22
	v_exp_f32_e32 v53, v17
	v_sub_f32_e32 v16, v16, v10
	v_add_f32_e32 v20, v100, v21
	v_exp_f32_e32 v55, v16
	v_sub_f32_e32 v15, v15, v10
	v_add_f32_e32 v19, v108, v20
	v_exp_f32_e32 v57, v15
	v_sub_f32_e32 v14, v14, v10
	v_add_f32_e32 v18, v52, v19
	v_exp_f32_e32 v58, v14
	v_sub_f32_e32 v13, v13, v10
	v_add_f32_e32 v17, v53, v18
	v_exp_f32_e32 v61, v13
	v_sub_f32_e32 v12, v12, v10
	v_add_f32_e32 v16, v55, v17
	v_exp_f32_e32 v64, v12
	v_sub_f32_e32 v11, v11, v10
	v_add_f32_e32 v15, v57, v16
	v_exp_f32_e32 v66, v11
	v_add_u32_e32 v106, v130, v132
	v_add_f32_e32 v14, v58, v15
	s_waitcnt lgkmcnt(0)
	v_mfma_f32_32x32x16_bf16 v[18:33], v[6:9], v[2:5], 0
	ds_read_b128 v[6:9], v106 offset:36864
	v_cvt_pk_bf16_f32 v170, v35, v36
	v_cvt_pk_bf16_f32 v171, v38, v39
	v_cvt_pk_bf16_f32 v172, v40, v45
	v_cvt_pk_bf16_f32 v173, v48, v51
	ds_read_b128 v[174:177], v105 offset:36896
	v_add_f32_e32 v13, v61, v14
	v_add_f32_e32 v12, v64, v13
	v_add_f32_e32 v11, v66, v12
	ds_bpermute_b32 v12, v129, v11
	v_fma_f32 v10, v149, s94, -v10
	v_exp_f32_e32 v10, v10
	s_waitcnt lgkmcnt(1)
	v_mfma_f32_32x32x16_bf16 v[18:33], v[174:177], v[170:173], v[18:33]
	s_waitcnt lgkmcnt(0)
	v_add_f32_e32 v11, v11, v12
	ds_read_b128 v[174:177], v106 offset:36896
	v_add_f32_e32 v34, v10, v11
	v_add_u32_e32 v107, v133, v131
	v_cvt_pk_bf16_f32 v36, v37, v41
	v_cvt_pk_bf16_f32 v37, v43, v44
	v_cvt_pk_bf16_f32 v38, v47, v56
	v_mfma_f32_32x32x16_bf16 v[2:17], v[6:9], v[2:5], 0
	v_cvt_pk_bf16_f32 v39, v62, v67
	v_add_u32_e32 v106, v133, v132
	v_add_u32_e32 v105, v134, v131
	v_div_scale_f32 v35, vcc, v34, v34, 1.0
	s_waitcnt lgkmcnt(0)
	v_mfma_f32_32x32x16_bf16 v[2:17], v[174:177], v[170:173], v[2:17]
	ds_read_b128 v[178:181], v107 offset:36864
	ds_read_b128 v[182:185], v106 offset:36864
	ds_read_b128 v[186:189], v107 offset:36896
	s_waitcnt lgkmcnt(2)
	v_mfma_f32_32x32x16_bf16 v[18:33], v[178:181], v[36:39], v[18:33]
	ds_read_b128 v[190:193], v106 offset:36896
	s_waitcnt lgkmcnt(2)
	v_mfma_f32_32x32x16_bf16 v[2:17], v[182:185], v[36:39], v[2:17]
	v_cvt_pk_bf16_f32 v36, v42, v46
	v_cvt_pk_bf16_f32 v37, v50, v54
	v_cvt_pk_bf16_f32 v38, v59, v69
	v_cvt_pk_bf16_f32 v39, v72, v78
	ds_read_b128 v[178:181], v105 offset:36864
	s_waitcnt lgkmcnt(2)
	v_mfma_f32_32x32x16_bf16 v[18:33], v[186:189], v[36:39], v[18:33]
	v_add_u32_e32 v194, v134, v132
	ds_read_b128 v[182:185], v194 offset:36864
	s_waitcnt lgkmcnt(2)
	v_mfma_f32_32x32x16_bf16 v[2:17], v[190:193], v[36:39], v[2:17]
	v_cvt_pk_bf16_f32 v36, v49, v60
	v_cvt_pk_bf16_f32 v37, v65, v68
	v_cvt_pk_bf16_f32 v38, v71, v98
	v_cvt_pk_bf16_f32 v39, v103, v104
	v_add_u32_e32 v104, v134, v132
	v_add_u32_e32 v103, v135, v131
	ds_read_b128 v[186:189], v105 offset:36896
	s_waitcnt lgkmcnt(2)
	v_mfma_f32_32x32x16_bf16 v[18:33], v[178:181], v[36:39], v[18:33]
	v_or_b32_e32 v98, s88, v152
	ds_read_b128 v[190:193], v104 offset:36896
	s_waitcnt lgkmcnt(2)
	v_mfma_f32_32x32x16_bf16 v[2:17], v[182:185], v[36:39], v[2:17]
	v_cvt_pk_bf16_f32 v36, v63, v70
	v_cvt_pk_bf16_f32 v37, v75, v80
	v_cvt_pk_bf16_f32 v38, v101, v155
	v_cvt_pk_bf16_f32 v39, v159, v163
	v_add_u32_e32 v101, v136, v131
	ds_read_b128 v[178:181], v103 offset:36864
	s_waitcnt lgkmcnt(2)
	v_mfma_f32_32x32x16_bf16 v[18:33], v[186:189], v[36:39], v[18:33]
	v_add_u32_e32 v202, v135, v132
	ds_read_b128 v[182:185], v202 offset:36864
	s_waitcnt lgkmcnt(2)
	v_mfma_f32_32x32x16_bf16 v[2:17], v[190:193], v[36:39], v[2:17]
	v_cvt_pk_bf16_f32 v36, v74, v102
	v_cvt_pk_bf16_f32 v37, v153, v154
	v_cvt_pk_bf16_f32 v38, v157, v166
	v_cvt_pk_bf16_f32 v39, v167, v168
	v_add_u32_e32 v102, v135, v132
	ds_read_b128 v[186:189], v103 offset:36896
	s_waitcnt lgkmcnt(2)
	v_mfma_f32_32x32x16_bf16 v[18:33], v[178:181], v[36:39], v[18:33]
	ds_read_b128 v[190:193], v102 offset:36896
	s_waitcnt lgkmcnt(2)
	v_mfma_f32_32x32x16_bf16 v[2:17], v[182:185], v[36:39], v[2:17]
	v_cvt_pk_bf16_f32 v36, v109, v156
	v_cvt_pk_bf16_f32 v37, v158, v160
	v_cvt_pk_bf16_f32 v38, v161, v162
	v_cvt_pk_bf16_f32 v39, v164, v165
	ds_read_b128 v[178:181], v101 offset:36864
	s_waitcnt lgkmcnt(2)
	v_mfma_f32_32x32x16_bf16 v[18:33], v[186:189], v[36:39], v[18:33]
	v_add_u32_e32 v203, v136, v132
	ds_read_b128 v[182:185], v203 offset:36864
	s_waitcnt lgkmcnt(2)
	v_mfma_f32_32x32x16_bf16 v[2:17], v[190:193], v[36:39], v[2:17]
	v_cvt_pk_bf16_f32 v36, v73, v76
	v_cvt_pk_bf16_f32 v37, v77, v79
	v_cvt_pk_bf16_f32 v38, v81, v99
	v_cvt_pk_bf16_f32 v39, v100, v108
	v_add_u32_e32 v100, v136, v132
	v_mov_b32_e32 v99, s89
	ds_read_b128 v[186:189], v101 offset:36896
	s_waitcnt lgkmcnt(2)
	v_mfma_f32_32x32x16_bf16 v[18:33], v[178:181], v[36:39], v[18:33]
	ds_read_b128 v[190:193], v100 offset:36896
	s_waitcnt lgkmcnt(2)
	v_mfma_f32_32x32x16_bf16 v[2:17], v[182:185], v[36:39], v[2:17]
	v_cvt_pk_bf16_f32 v36, v52, v53
	v_cvt_pk_bf16_f32 v37, v55, v57
	v_cvt_pk_bf16_f32 v38, v58, v61
	v_cvt_pk_bf16_f32 v39, v64, v66
	s_waitcnt lgkmcnt(1)
	v_mfma_f32_32x32x16_bf16 v[18:33], v[186:189], v[36:39], v[18:33]
	s_waitcnt lgkmcnt(0)
	v_mfma_f32_32x32x16_bf16 v[2:17], v[190:193], v[36:39], v[2:17]
	v_rcp_f32_e32 v36, v35
	s_nop 0
	v_fma_f32 v37, -v35, v36, 1.0
	v_fmac_f32_e32 v36, v37, v36
	v_div_scale_f32 v37, vcc, 1.0, v34, 1.0
	v_mul_f32_e32 v38, v37, v36
	v_fma_f32 v39, -v35, v38, v37
	v_fmac_f32_e32 v38, v39, v36
	v_fma_f32 v35, -v35, v38, v37
	v_div_fmas_f32 v35, v35, v36, v38
	v_div_fixup_f32 v36, v35, v34, 1.0
	v_mul_f32_e32 v18, v18, v36
	v_mul_f32_e32 v19, v19, v36
	v_lshlrev_b64 v[34:35], 11, v[98:99]
	v_cvt_pk_bf16_f32 v18, v18, v19
	v_mul_f32_e32 v19, v20, v36
	v_lshl_add_u64 v[34:35], v[126:127], 0, v[34:35]
	v_mul_f32_e32 v20, v21, v36
	v_cvt_pk_bf16_f32 v19, v19, v20
	global_store_dwordx2 v[34:35], v[18:19], off
	v_mul_f32_e32 v18, v22, v36
	v_mul_f32_e32 v19, v23, v36
	v_cvt_pk_bf16_f32 v18, v18, v19
	v_mul_f32_e32 v19, v24, v36
	v_mul_f32_e32 v20, v25, v36
	v_cvt_pk_bf16_f32 v19, v19, v20
	global_store_dwordx2 v[34:35], v[18:19], off offset:16
	v_mul_f32_e32 v18, v26, v36
	v_mul_f32_e32 v19, v27, v36
	v_cvt_pk_bf16_f32 v18, v18, v19
	v_mul_f32_e32 v19, v28, v36
	v_mul_f32_e32 v20, v29, v36
	v_cvt_pk_bf16_f32 v19, v19, v20
	global_store_dwordx2 v[34:35], v[18:19], off offset:32
	v_mul_f32_e32 v18, v30, v36
	v_mul_f32_e32 v19, v31, v36
	v_cvt_pk_bf16_f32 v18, v18, v19
	v_mul_f32_e32 v19, v32, v36
	v_mul_f32_e32 v2, v2, v36
	v_mul_f32_e32 v3, v3, v36
	v_mul_f32_e32 v20, v33, v36
	v_cvt_pk_bf16_f32 v19, v19, v20
	global_store_dwordx2 v[34:35], v[18:19], off offset:48
	v_cvt_pk_bf16_f32 v2, v2, v3
	v_mul_f32_e32 v3, v4, v36
	v_mul_f32_e32 v4, v5, v36
	v_cvt_pk_bf16_f32 v3, v3, v4
	global_store_dwordx2 v[34:35], v[2:3], off offset:64
	v_mul_f32_e32 v2, v6, v36
	v_mul_f32_e32 v3, v7, v36
	v_cvt_pk_bf16_f32 v2, v2, v3
	v_mul_f32_e32 v3, v8, v36
	v_mul_f32_e32 v4, v9, v36
	v_cvt_pk_bf16_f32 v3, v3, v4
	global_store_dwordx2 v[34:35], v[2:3], off offset:80
	v_mul_f32_e32 v2, v10, v36
	v_mul_f32_e32 v3, v11, v36
	v_cvt_pk_bf16_f32 v2, v2, v3
	v_mul_f32_e32 v3, v12, v36
	v_mul_f32_e32 v4, v13, v36
	v_cvt_pk_bf16_f32 v3, v3, v4
	global_store_dwordx2 v[34:35], v[2:3], off offset:96
	v_mul_f32_e32 v2, v14, v36
	v_mul_f32_e32 v3, v15, v36
	v_cvt_pk_bf16_f32 v2, v2, v3
	v_mul_f32_e32 v3, v16, v36
	v_mul_f32_e32 v4, v17, v36
	v_cvt_pk_bf16_f32 v3, v3, v4
	global_store_dwordx2 v[34:35], v[2:3], off offset:112
	ds_read_b128 v[2:5], v143
	ds_read_b128 v[6:9], v143 offset:32
	s_waitcnt lgkmcnt(1)
	v_mfma_f32_32x32x16_bf16 v[66:81], v[2:5], v[94:97], 0
	ds_read_b128 v[2:5], v143 offset:64
	v_or_b32_e32 v98, s87, v150
	v_or_b32_e32 v98, s88, v98
	s_waitcnt lgkmcnt(1)
	v_mfma_f32_32x32x16_bf16 v[66:81], v[6:9], v[90:93], v[66:81]
	s_waitcnt lgkmcnt(0)
	v_mfma_f32_32x32x16_bf16 v[66:81], v[2:5], v[86:89], v[66:81]
	ds_read_b128 v[2:5], v143 offset:96
	s_waitcnt lgkmcnt(0)
	v_mfma_f32_32x32x16_bf16 v[66:81], v[2:5], v[82:85], v[66:81]
	ds_read_b128 v[2:5], v144
	ds_read_b128 v[6:9], v144 offset:32
	s_waitcnt lgkmcnt(1)
	v_mfma_f32_32x32x16_bf16 v[34:49], v[2:5], v[94:97], 0
	ds_read_b128 v[2:5], v144 offset:64
	s_nop 6
	v_cndmask_b32_e64 v66, v245, v66, s[48:49]
	v_cndmask_b32_e64 v68, v245, v68, s[52:53]
	v_cndmask_b32_e64 v69, v245, v69, s[54:55]
	v_cndmask_b32_e64 v70, v245, v70, s[56:57]
	v_cndmask_b32_e64 v71, v245, v71, s[58:59]
	v_cndmask_b32_e64 v72, v245, v72, s[60:61]
	s_waitcnt lgkmcnt(1)
	v_mfma_f32_32x32x16_bf16 v[34:49], v[6:9], v[90:93], v[34:49]
	v_cndmask_b32_e64 v73, v245, v73, s[62:63]
	v_cndmask_b32_e64 v74, v245, v74, s[64:65]
	v_cndmask_b32_e64 v75, v245, v75, s[66:67]
	v_cndmask_b32_e64 v76, v245, v76, s[68:69]
	v_cndmask_b32_e64 v77, v245, v77, s[70:71]
	v_cndmask_b32_e64 v78, v245, v78, s[72:73]
	v_cndmask_b32_e64 v79, v245, v79, s[74:75]
	s_waitcnt lgkmcnt(0)
	v_mfma_f32_32x32x16_bf16 v[34:49], v[2:5], v[86:89], v[34:49]
	ds_read_b128 v[2:5], v144 offset:96
	v_cndmask_b32_e64 v80, v245, v80, s[76:77]
	v_cndmask_b32_e64 v81, v245, v81, s[78:79]
	s_waitcnt lgkmcnt(0)
	v_mfma_f32_32x32x16_bf16 v[34:49], v[2:5], v[82:85], v[34:49]
	ds_read_b128 v[2:5], v145
	ds_read_b128 v[6:9], v145 offset:32
	s_waitcnt lgkmcnt(1)
	v_mfma_f32_32x32x16_bf16 v[18:33], v[2:5], v[94:97], 0
	ds_read_b128 v[2:5], v145 offset:64
	s_nop 6
	v_cndmask_b32_e64 v42, v42, v245, s[80:81]
	s_waitcnt lgkmcnt(1)
	v_mfma_f32_32x32x16_bf16 v[18:33], v[6:9], v[90:93], v[18:33]
	s_waitcnt lgkmcnt(0)
	v_mfma_f32_32x32x16_bf16 v[18:33], v[2:5], v[86:89], v[18:33]
	ds_read_b128 v[2:5], v145 offset:96
	s_waitcnt lgkmcnt(0)
	v_mfma_f32_32x32x16_bf16 v[18:33], v[2:5], v[82:85], v[18:33]
	ds_read_b128 v[2:5], v146
	ds_read_b128 v[50:53], v146 offset:32
	s_waitcnt lgkmcnt(1)
	v_mfma_f32_32x32x16_bf16 v[2:17], v[2:5], v[94:97], 0
	s_nop 7
	v_cndmask_b32_e64 v108, v18, v245, s[80:81]
	v_cndmask_b32_e64 v109, v19, v245, s[80:81]
	v_cndmask_b32_e64 v150, v20, v245, s[80:81]
	v_cndmask_b32_e64 v156, v26, v245, s[80:81]
	v_cndmask_b32_e64 v157, v27, v245, s[80:81]
	v_cndmask_b32_e64 v158, v28, v245, s[80:81]
	v_cndmask_b32_e64 v159, v29, v245, s[80:81]
	s_waitcnt lgkmcnt(0)
	v_mfma_f32_32x32x16_bf16 v[2:17], v[50:53], v[90:93], v[2:17]
	ds_read_b128 v[50:53], v146 offset:64
	v_cndmask_b32_e64 v160, v30, v245, s[80:81]
	v_cndmask_b32_e64 v161, v31, v245, s[80:81]
	v_cndmask_b32_e64 v162, v32, v245, s[80:81]
	v_cndmask_b32_e64 v163, v33, v245, s[80:81]
	s_waitcnt lgkmcnt(0)
	v_mfma_f32_32x32x16_bf16 v[2:17], v[50:53], v[86:89], v[2:17]
	ds_read_b128 v[50:53], v146 offset:96
	s_waitcnt lgkmcnt(0)
	v_mfma_f32_32x32x16_bf16 v[2:17], v[50:53], v[82:85], v[2:17]
	ds_read_b128 v[50:53], v147
	ds_read_b128 v[152:155], v147 offset:32
	s_waitcnt lgkmcnt(1)
	v_mfma_f32_32x32x16_bf16 v[50:65], v[50:53], v[94:97], 0
	v_cndmask_b32_e64 v94, v46, v245, s[80:81]
	v_cndmask_b32_e64 v95, v47, v245, s[80:81]
	v_cndmask_b32_e64 v96, v48, v245, s[80:81]
	v_cndmask_b32_e64 v97, v49, v245, s[80:81]
	s_waitcnt lgkmcnt(0)
	v_mfma_f32_32x32x16_bf16 v[50:65], v[152:155], v[90:93], v[50:65]
	ds_read_b128 v[90:93], v147 offset:64
	v_cndmask_b32_e64 v152, v22, v245, s[80:81]
	v_cndmask_b32_e64 v153, v23, v245, s[80:81]
	v_cndmask_b32_e64 v154, v24, v245, s[80:81]
	v_cndmask_b32_e64 v155, v25, v245, s[80:81]
	s_waitcnt lgkmcnt(0)
	v_mfma_f32_32x32x16_bf16 v[50:65], v[90:93], v[86:89], v[50:65]
	ds_read_b128 v[86:89], v147 offset:96
	v_cndmask_b32_e64 v90, v41, v245, s[80:81]
	v_cndmask_b32_e64 v91, v43, v245, s[80:81]
	v_cndmask_b32_e64 v92, v44, v245, s[80:81]
	v_cndmask_b32_e64 v93, v45, v245, s[80:81]
	s_waitcnt lgkmcnt(0)
	v_mfma_f32_32x32x16_bf16 v[50:65], v[86:89], v[82:85], v[50:65]
	v_cndmask_b32_e64 v82, v245, v67, s[50:51]
	v_max3_f32 v67, v151, v66, v82
	v_max3_f32 v67, v67, v68, v69
	v_max3_f32 v67, v67, v70, v71
	v_max3_f32 v67, v67, v72, v73
	v_max3_f32 v67, v67, v74, v75
	v_max3_f32 v67, v67, v76, v77
	v_max3_f32 v67, v67, v78, v79
	v_max3_f32 v67, v67, v80, v81
	v_cndmask_b32_e64 v83, v34, v245, s[80:81]
	v_cndmask_b32_e64 v84, v35, v245, s[80:81]
	v_max3_f32 v34, v67, v83, v84
	v_cndmask_b32_e64 v85, v36, v245, s[80:81]
	v_cndmask_b32_e64 v86, v37, v245, s[80:81]
	v_max3_f32 v34, v34, v85, v86
	v_cndmask_b32_e64 v87, v38, v245, s[80:81]
	v_cndmask_b32_e64 v88, v39, v245, s[80:81]
	v_max3_f32 v34, v34, v87, v88
	v_cndmask_b32_e64 v89, v40, v245, s[80:81]
	v_max3_f32 v34, v34, v89, v90
	v_max3_f32 v34, v34, v42, v91
	v_max3_f32 v34, v34, v92, v93
	v_max3_f32 v34, v34, v94, v95
	v_max3_f32 v34, v34, v96, v97
	v_max3_f32 v18, v34, v108, v109
	v_cndmask_b32_e64 v151, v21, v245, s[80:81]
	v_max3_f32 v18, v18, v150, v151
	v_max3_f32 v18, v18, v152, v153
	v_max3_f32 v18, v18, v154, v155
	v_max3_f32 v18, v18, v156, v157
	v_max3_f32 v18, v18, v158, v159
	v_max3_f32 v18, v18, v160, v161
	v_max3_f32 v18, v18, v162, v163
	v_max3_f32 v18, v18, v2, v3
	v_max3_f32 v18, v18, v4, v5
	v_max3_f32 v18, v18, v6, v7
	v_max3_f32 v18, v18, v8, v9
	v_max3_f32 v18, v18, v10, v11
	v_max3_f32 v18, v18, v12, v13
	v_max3_f32 v18, v18, v14, v15
	v_max3_f32 v18, v18, v16, v17
	v_cndmask_b32_e64 v67, v50, v245, s[12:13]
	v_cndmask_b32_e64 v50, v245, v51, s[46:47]
	v_max3_f32 v18, v18, v67, v50
	v_cndmask_b32_e64 v49, v52, v245, s[16:17]
	v_cndmask_b32_e64 v48, v53, v245, s[18:19]
	v_max3_f32 v18, v18, v49, v48
	v_cndmask_b32_e64 v47, v54, v245, s[20:21]
	v_cndmask_b32_e64 v45, v55, v245, s[22:23]
	v_max3_f32 v18, v18, v47, v45
	v_cndmask_b32_e64 v43, v56, v245, s[24:25]
	v_cndmask_b32_e64 v40, v57, v245, s[26:27]
	v_max3_f32 v18, v18, v43, v40
	v_cndmask_b32_e64 v34, v58, v245, s[28:29]
	v_cndmask_b32_e64 v33, v59, v245, s[30:31]
	v_max3_f32 v18, v18, v34, v33
	v_cndmask_b32_e64 v32, v60, v245, s[34:35]
	v_cndmask_b32_e64 v31, v61, v245, s[36:37]
	v_max3_f32 v18, v18, v32, v31
	v_cndmask_b32_e64 v30, v62, v245, s[38:39]
	v_cndmask_b32_e64 v29, v63, v245, s[42:43]
	v_max3_f32 v18, v18, v30, v29
	v_cndmask_b32_e64 v28, v64, v245, s[44:45]
	v_cndmask_b32_e64 v27, v65, v245, s[0:1]
	v_max3_f32 v18, v18, v28, v27
	ds_bpermute_b32 v19, v129, v18
	s_waitcnt lgkmcnt(0)
	v_max_f32_e32 v19, v19, v19
	v_max_f32_e32 v26, v18, v19
	v_sub_f32_e32 v18, v66, v26
	v_exp_f32_e32 v18, v18
	v_sub_f32_e32 v19, v82, v26
	v_exp_f32_e32 v19, v19
	v_sub_f32_e32 v38, v76, v26
	v_add_f32_e32 v20, 0, v18
	v_exp_f32_e32 v38, v38
	v_add_f32_e32 v21, v19, v20
	v_sub_f32_e32 v20, v68, v26
	v_exp_f32_e32 v20, v20
	v_sub_f32_e32 v39, v77, v26
	v_exp_f32_e32 v39, v39
	v_sub_f32_e32 v41, v78, v26
	v_add_f32_e32 v22, v20, v21
	v_sub_f32_e32 v21, v69, v26
	v_exp_f32_e32 v21, v21
	v_exp_f32_e32 v44, v41
	v_sub_f32_e32 v41, v79, v26
	v_exp_f32_e32 v54, v41
	v_add_f32_e32 v23, v21, v22
	v_sub_f32_e32 v22, v70, v26
	v_exp_f32_e32 v22, v22
	v_sub_f32_e32 v41, v80, v26
	v_exp_f32_e32 v58, v41
	v_sub_f32_e32 v41, v81, v26
	v_add_f32_e32 v24, v22, v23
	v_sub_f32_e32 v23, v71, v26
	v_exp_f32_e32 v23, v23
	v_exp_f32_e32 v60, v41
	v_sub_f32_e32 v53, v87, v26
	v_exp_f32_e32 v56, v53
	v_add_f32_e32 v25, v23, v24
	v_sub_f32_e32 v24, v72, v26
	v_exp_f32_e32 v24, v24
	v_sub_f32_e32 v53, v88, v26
	v_exp_f32_e32 v63, v53
	v_sub_f32_e32 v53, v89, v26
	v_add_f32_e32 v35, v24, v25
	v_sub_f32_e32 v25, v73, v26
	v_exp_f32_e32 v25, v25
	v_exp_f32_e32 v70, v53
	v_sub_f32_e32 v53, v90, v26
	v_sub_f32_e32 v42, v42, v26
	v_add_f32_e32 v36, v25, v35
	v_sub_f32_e32 v35, v74, v26
	v_exp_f32_e32 v35, v35
	v_exp_f32_e32 v42, v42
	v_sub_f32_e32 v55, v92, v26
	v_exp_f32_e32 v57, v55
	v_add_f32_e32 v37, v35, v36
	v_sub_f32_e32 v36, v75, v26
	v_exp_f32_e32 v36, v36
	v_exp_f32_e32 v75, v53
	v_sub_f32_e32 v53, v91, v26
	v_exp_f32_e32 v53, v53
	v_add_f32_e32 v37, v36, v37
	v_add_f32_e32 v37, v38, v37
	v_add_f32_e32 v37, v39, v37
	v_add_f32_e32 v37, v44, v37
	v_add_f32_e32 v37, v54, v37
	v_add_f32_e32 v37, v58, v37
	v_add_f32_e32 v41, v60, v37
	v_sub_f32_e32 v37, v83, v26
	v_exp_f32_e32 v37, v37
	v_sub_f32_e32 v55, v93, v26
	v_exp_f32_e32 v59, v55
	v_sub_f32_e32 v55, v94, v26
	v_add_f32_e32 v46, v37, v41
	v_sub_f32_e32 v41, v84, v26
	v_exp_f32_e32 v41, v41
	v_exp_f32_e32 v66, v55
	v_sub_f32_e32 v55, v95, v26
	v_exp_f32_e32 v78, v55
	v_add_f32_e32 v51, v41, v46
	v_sub_f32_e32 v46, v85, v26
	v_exp_f32_e32 v46, v46
	v_sub_f32_e32 v55, v96, v26
	v_exp_f32_e32 v82, v55
	v_sub_f32_e32 v55, v97, v26
	v_add_f32_e32 v52, v46, v51
	v_sub_f32_e32 v51, v86, v26
	v_exp_f32_e32 v51, v51
	v_exp_f32_e32 v85, v55
	v_sub_f32_e32 v55, v108, v26
	v_exp_f32_e32 v55, v55
	v_add_f32_e32 v52, v51, v52
	v_add_f32_e32 v52, v56, v52
	v_add_f32_e32 v52, v63, v52
	v_add_f32_e32 v52, v70, v52
	v_add_f32_e32 v52, v75, v52
	v_add_f32_e32 v52, v42, v52
	v_add_f32_e32 v52, v53, v52
	v_add_f32_e32 v52, v57, v52
	v_add_f32_e32 v52, v59, v52
	v_add_f32_e32 v52, v66, v52
	v_sub_f32_e32 v61, v109, v26
	v_add_f32_e32 v52, v78, v52
	v_exp_f32_e32 v62, v61
	v_sub_f32_e32 v61, v150, v26
	v_add_f32_e32 v52, v82, v52
	v_exp_f32_e32 v68, v61
	v_sub_f32_e32 v61, v151, v26
	v_add_f32_e32 v52, v85, v52
	v_exp_f32_e32 v74, v61
	v_sub_f32_e32 v61, v152, v26
	v_add_f32_e32 v52, v55, v52
	v_exp_f32_e32 v80, v61
	v_sub_f32_e32 v61, v153, v26
	v_add_f32_e32 v52, v62, v52
	v_exp_f32_e32 v88, v61
	v_sub_f32_e32 v61, v154, v26
	v_add_f32_e32 v52, v68, v52
	v_exp_f32_e32 v94, v61
	v_sub_f32_e32 v61, v155, v26
	v_add_f32_e32 v52, v74, v52
	v_exp_f32_e32 v109, v61
	v_sub_f32_e32 v61, v156, v26
	v_add_f32_e32 v52, v80, v52
	v_exp_f32_e32 v64, v61
	v_sub_f32_e32 v61, v157, v26
	v_add_f32_e32 v52, v88, v52
	v_exp_f32_e32 v77, v61
	v_sub_f32_e32 v61, v158, v26
	v_add_f32_e32 v52, v94, v52
	v_exp_f32_e32 v81, v61
	v_sub_f32_e32 v61, v159, v26
	v_add_f32_e32 v52, v109, v52
	v_exp_f32_e32 v83, v61
	v_sub_f32_e32 v61, v160, v26
	v_add_f32_e32 v52, v64, v52
	v_exp_f32_e32 v90, v61
	v_sub_f32_e32 v61, v161, v26
	v_add_f32_e32 v52, v77, v52
	v_exp_f32_e32 v150, v61
	v_sub_f32_e32 v61, v162, v26
	v_add_f32_e32 v52, v81, v52
	v_exp_f32_e32 v152, v61
	v_sub_f32_e32 v61, v163, v26
	v_add_f32_e32 v52, v83, v52
	v_exp_f32_e32 v153, v61
	v_sub_f32_e32 v2, v2, v26
	v_add_f32_e32 v52, v90, v52
	v_exp_f32_e32 v79, v2
	v_sub_f32_e32 v3, v3, v26
	v_add_f32_e32 v52, v150, v52
	v_exp_f32_e32 v86, v3
	v_sub_f32_e32 v3, v4, v26
	v_add_f32_e32 v52, v152, v52
	v_exp_f32_e32 v92, v3
	v_sub_f32_e32 v3, v5, v26
	v_add_f32_e32 v52, v153, v52
	v_exp_f32_e32 v97, v3
	v_sub_f32_e32 v3, v6, v26
	v_add_f32_e32 v2, v79, v52
	v_exp_f32_e32 v151, v3
	v_sub_f32_e32 v3, v7, v26
	v_add_f32_e32 v2, v86, v2
	v_exp_f32_e32 v154, v3
	v_sub_f32_e32 v3, v8, v26
	v_add_f32_e32 v2, v92, v2
	v_exp_f32_e32 v155, v3
	v_sub_f32_e32 v3, v9, v26
	v_add_f32_e32 v2, v97, v2
	v_exp_f32_e32 v156, v3
	v_sub_f32_e32 v3, v10, v26
	v_add_f32_e32 v2, v151, v2
	v_exp_f32_e32 v84, v3
	v_sub_f32_e32 v3, v11, v26
	v_add_f32_e32 v2, v154, v2
	v_exp_f32_e32 v87, v3
	v_sub_f32_e32 v3, v12, v26
	v_add_f32_e32 v2, v155, v2
	v_exp_f32_e32 v89, v3
	v_sub_f32_e32 v3, v13, v26
	v_add_f32_e32 v2, v156, v2
	v_exp_f32_e32 v91, v3
	v_sub_f32_e32 v3, v14, v26
	v_add_f32_e32 v2, v84, v2
	v_exp_f32_e32 v93, v3
	v_sub_f32_e32 v3, v15, v26
	v_add_f32_e32 v2, v87, v2
	v_exp_f32_e32 v95, v3
	v_sub_f32_e32 v3, v16, v26
	v_add_f32_e32 v2, v89, v2
	v_exp_f32_e32 v96, v3
	v_sub_f32_e32 v3, v17, v26
	v_add_f32_e32 v2, v91, v2
	v_exp_f32_e32 v108, v3
	v_sub_f32_e32 v3, v67, v26
	v_add_f32_e32 v2, v93, v2
	v_exp_f32_e32 v61, v3
	v_sub_f32_e32 v3, v50, v26
	v_add_f32_e32 v2, v95, v2
	v_exp_f32_e32 v65, v3
	v_sub_f32_e32 v3, v49, v26
	v_add_f32_e32 v2, v96, v2
	v_exp_f32_e32 v67, v3
	v_sub_f32_e32 v3, v48, v26
	v_add_f32_e32 v2, v108, v2
	v_exp_f32_e32 v69, v3
	v_sub_f32_e32 v3, v47, v26
	v_add_f32_e32 v2, v61, v2
	v_exp_f32_e32 v71, v3
	v_sub_f32_e32 v3, v45, v26
	v_add_f32_e32 v2, v65, v2
	v_exp_f32_e32 v72, v3
	v_sub_f32_e32 v3, v43, v26
	v_add_f32_e32 v2, v67, v2
	v_exp_f32_e32 v73, v3
	v_sub_f32_e32 v3, v40, v26
	v_add_f32_e32 v2, v69, v2
	v_exp_f32_e32 v76, v3
	v_sub_f32_e32 v3, v34, v26
	v_add_f32_e32 v2, v71, v2
	v_exp_f32_e32 v40, v3
	v_sub_f32_e32 v3, v33, v26
	v_add_f32_e32 v2, v72, v2
	v_exp_f32_e32 v43, v3
	v_sub_f32_e32 v3, v32, v26
	v_add_f32_e32 v2, v73, v2
	v_exp_f32_e32 v45, v3
	v_sub_f32_e32 v3, v31, v26
	v_add_f32_e32 v2, v76, v2
	v_exp_f32_e32 v47, v3
	v_sub_f32_e32 v3, v30, v26
	v_add_f32_e32 v2, v40, v2
	v_exp_f32_e32 v48, v3
	v_sub_f32_e32 v3, v29, v26
	v_add_f32_e32 v2, v43, v2
	v_exp_f32_e32 v49, v3
	v_sub_f32_e32 v3, v28, v26
	v_add_f32_e32 v2, v45, v2
	v_exp_f32_e32 v50, v3
	v_sub_f32_e32 v3, v27, v26
	v_add_f32_e32 v2, v47, v2
	v_exp_f32_e32 v52, v3
	v_add_f32_e32 v2, v48, v2
	v_add_f32_e32 v2, v49, v2
	v_add_f32_e32 v2, v50, v2
	v_add_f32_e32 v2, v52, v2
	ds_bpermute_b32 v3, v129, v2
	s_waitcnt lgkmcnt(0)
	v_add_f32_e32 v2, v2, v3
	v_fma_f32 v3, v149, s94, -v26
	v_exp_f32_e32 v3, v3
	s_nop 0
	v_add_f32_e32 v34, v3, v2
	v_cvt_pk_bf16_f32 v2, v18, v19
	v_cvt_pk_bf16_f32 v3, v20, v21
	v_cvt_pk_bf16_f32 v4, v22, v23
	v_cvt_pk_bf16_f32 v5, v24, v25
	ds_read_b128 v[6:9], v107 offset:36864
	s_waitcnt lgkmcnt(0)
	v_mfma_f32_32x32x16_bf16 v[18:33], v[6:9], v[2:5], 0
	ds_read_b128 v[6:9], v106 offset:36864
	v_cvt_pk_bf16_f32 v158, v35, v36
	v_cvt_pk_bf16_f32 v159, v38, v39
	v_cvt_pk_bf16_f32 v160, v44, v54
	v_cvt_pk_bf16_f32 v161, v58, v60
	ds_read_b128 v[162:165], v107 offset:36896
	v_add_u32_e32 v35, v137, v131
	s_waitcnt lgkmcnt(0)
	v_mfma_f32_32x32x16_bf16 v[18:33], v[162:165], v[158:161], v[18:33]
	ds_read_b128 v[162:165], v106 offset:36896
	v_cvt_pk_bf16_f32 v36, v37, v41
	v_cvt_pk_bf16_f32 v37, v46, v51
	v_cvt_pk_bf16_f32 v38, v56, v63
	v_cvt_pk_bf16_f32 v39, v70, v75
	v_add_u32_e32 v44, v137, v132
	v_mfma_f32_32x32x16_bf16 v[2:17], v[6:9], v[2:5], 0
	s_waitcnt lgkmcnt(0)
	v_mfma_f32_32x32x16_bf16 v[2:17], v[162:165], v[158:161], v[2:17]
	ds_read_b128 v[178:181], v105 offset:36864
	ds_read_b128 v[182:185], v104 offset:36864
	ds_read_b128 v[186:189], v105 offset:36896
	s_waitcnt lgkmcnt(2)
	v_mfma_f32_32x32x16_bf16 v[18:33], v[178:181], v[36:39], v[18:33]
	ds_read_b128 v[190:193], v104 offset:36896
	s_waitcnt lgkmcnt(2)
	v_mfma_f32_32x32x16_bf16 v[2:17], v[182:185], v[36:39], v[2:17]
	v_cvt_pk_bf16_f32 v36, v42, v53
	v_cvt_pk_bf16_f32 v37, v57, v59
	v_cvt_pk_bf16_f32 v38, v66, v78
	v_cvt_pk_bf16_f32 v39, v82, v85
	ds_read_b128 v[178:181], v103 offset:36864
	s_waitcnt lgkmcnt(2)
	v_mfma_f32_32x32x16_bf16 v[18:33], v[186:189], v[36:39], v[18:33]
	ds_read_b128 v[182:185], v102 offset:36864
	s_waitcnt lgkmcnt(2)
	v_mfma_f32_32x32x16_bf16 v[2:17], v[190:193], v[36:39], v[2:17]
	v_cvt_pk_bf16_f32 v36, v55, v62
	v_cvt_pk_bf16_f32 v37, v68, v74
	v_cvt_pk_bf16_f32 v38, v80, v88
	v_cvt_pk_bf16_f32 v39, v94, v109
	ds_read_b128 v[186:189], v103 offset:36896
	s_waitcnt lgkmcnt(2)
	v_mfma_f32_32x32x16_bf16 v[18:33], v[178:181], v[36:39], v[18:33]
	ds_read_b128 v[190:193], v102 offset:36896
	s_waitcnt lgkmcnt(2)
	v_mfma_f32_32x32x16_bf16 v[2:17], v[182:185], v[36:39], v[2:17]
	v_cvt_pk_bf16_f32 v36, v64, v77
	v_cvt_pk_bf16_f32 v37, v81, v83
	v_cvt_pk_bf16_f32 v38, v90, v150
	v_cvt_pk_bf16_f32 v39, v152, v153
	ds_read_b128 v[178:181], v101 offset:36864
	s_waitcnt lgkmcnt(2)
	v_mfma_f32_32x32x16_bf16 v[18:33], v[186:189], v[36:39], v[18:33]
	ds_read_b128 v[182:185], v100 offset:36864
	s_waitcnt lgkmcnt(2)
	v_mfma_f32_32x32x16_bf16 v[2:17], v[190:193], v[36:39], v[2:17]
	v_cvt_pk_bf16_f32 v36, v79, v86
	v_cvt_pk_bf16_f32 v37, v92, v97
	v_cvt_pk_bf16_f32 v38, v151, v154
	v_cvt_pk_bf16_f32 v39, v155, v156
	ds_read_b128 v[186:189], v101 offset:36896
	s_waitcnt lgkmcnt(2)
	v_mfma_f32_32x32x16_bf16 v[18:33], v[178:181], v[36:39], v[18:33]
	ds_read_b128 v[190:193], v100 offset:36896
	s_waitcnt lgkmcnt(2)
	v_mfma_f32_32x32x16_bf16 v[2:17], v[182:185], v[36:39], v[2:17]
	v_cvt_pk_bf16_f32 v36, v84, v87
	v_cvt_pk_bf16_f32 v37, v89, v91
	v_cvt_pk_bf16_f32 v38, v93, v95
	v_cvt_pk_bf16_f32 v39, v96, v108
	ds_read_b128 v[178:181], v35 offset:36864
	s_waitcnt lgkmcnt(2)
	v_mfma_f32_32x32x16_bf16 v[18:33], v[186:189], v[36:39], v[18:33]
	ds_read_b128 v[182:185], v44 offset:36864
	s_waitcnt lgkmcnt(2)
	v_mfma_f32_32x32x16_bf16 v[2:17], v[190:193], v[36:39], v[2:17]
	v_cvt_pk_bf16_f32 v36, v61, v65
	v_cvt_pk_bf16_f32 v37, v67, v69
	v_cvt_pk_bf16_f32 v38, v71, v72
	v_cvt_pk_bf16_f32 v39, v73, v76
	ds_read_b128 v[186:189], v35 offset:36896
	s_waitcnt lgkmcnt(2)
	v_mfma_f32_32x32x16_bf16 v[18:33], v[178:181], v[36:39], v[18:33]
	ds_read_b128 v[190:193], v44 offset:36896
	s_waitcnt lgkmcnt(2)
	v_mfma_f32_32x32x16_bf16 v[2:17], v[182:185], v[36:39], v[2:17]
	v_cvt_pk_bf16_f32 v36, v40, v43
	v_cvt_pk_bf16_f32 v37, v45, v47
	v_cvt_pk_bf16_f32 v38, v48, v49
	v_cvt_pk_bf16_f32 v39, v50, v52
	v_div_scale_f32 v35, s[48:49], v34, v34, 1.0
	s_waitcnt lgkmcnt(1)
	v_mfma_f32_32x32x16_bf16 v[18:33], v[186:189], v[36:39], v[18:33]
	s_waitcnt lgkmcnt(0)
	v_mfma_f32_32x32x16_bf16 v[2:17], v[190:193], v[36:39], v[2:17]
	v_rcp_f32_e32 v36, v35
	s_nop 0
	v_fma_f32 v37, -v35, v36, 1.0
	v_fmac_f32_e32 v36, v37, v36
	v_div_scale_f32 v37, vcc, 1.0, v34, 1.0
	v_mul_f32_e32 v38, v37, v36
	v_fma_f32 v39, -v35, v38, v37
	v_fmac_f32_e32 v38, v39, v36
	v_fma_f32 v35, -v35, v38, v37
	v_div_fmas_f32 v35, v35, v36, v38
	v_div_fixup_f32 v36, v35, v34, 1.0
	v_mul_f32_e32 v18, v18, v36
	v_mul_f32_e32 v19, v19, v36
	v_lshlrev_b64 v[34:35], 11, v[98:99]
	v_cvt_pk_bf16_f32 v18, v18, v19
	v_mul_f32_e32 v19, v20, v36
	v_lshl_add_u64 v[34:35], v[126:127], 0, v[34:35]
	v_mul_f32_e32 v20, v21, v36
	v_cvt_pk_bf16_f32 v19, v19, v20
	global_store_dwordx2 v[34:35], v[18:19], off
	v_mul_f32_e32 v18, v22, v36
	v_mul_f32_e32 v19, v23, v36
	v_cvt_pk_bf16_f32 v18, v18, v19
	v_mul_f32_e32 v19, v24, v36
	v_mul_f32_e32 v20, v25, v36
	v_cvt_pk_bf16_f32 v19, v19, v20
	global_store_dwordx2 v[34:35], v[18:19], off offset:16
	v_mul_f32_e32 v18, v26, v36
	v_mul_f32_e32 v19, v27, v36
	v_cvt_pk_bf16_f32 v18, v18, v19
	v_mul_f32_e32 v19, v28, v36
	v_mul_f32_e32 v20, v29, v36
	v_cvt_pk_bf16_f32 v19, v19, v20
	global_store_dwordx2 v[34:35], v[18:19], off offset:32
	v_mul_f32_e32 v18, v30, v36
	v_mul_f32_e32 v19, v31, v36
	v_cvt_pk_bf16_f32 v18, v18, v19
	v_mul_f32_e32 v19, v32, v36
	v_mul_f32_e32 v2, v2, v36
	v_mul_f32_e32 v3, v3, v36
	v_mul_f32_e32 v20, v33, v36
	v_cvt_pk_bf16_f32 v19, v19, v20
	global_store_dwordx2 v[34:35], v[18:19], off offset:48
	v_cvt_pk_bf16_f32 v2, v2, v3
	v_mul_f32_e32 v3, v4, v36
	v_mul_f32_e32 v4, v5, v36
	v_cvt_pk_bf16_f32 v3, v3, v4
	global_store_dwordx2 v[34:35], v[2:3], off offset:64
	v_mul_f32_e32 v2, v6, v36
	v_mul_f32_e32 v3, v7, v36
	v_cvt_pk_bf16_f32 v2, v2, v3
	v_mul_f32_e32 v3, v8, v36
	v_mul_f32_e32 v4, v9, v36
	v_cvt_pk_bf16_f32 v3, v3, v4
	global_store_dwordx2 v[34:35], v[2:3], off offset:80
	v_mul_f32_e32 v2, v10, v36
	v_mul_f32_e32 v3, v11, v36
	v_cvt_pk_bf16_f32 v2, v2, v3
	v_mul_f32_e32 v3, v12, v36
	v_mul_f32_e32 v4, v13, v36
	v_cvt_pk_bf16_f32 v3, v3, v4
	global_store_dwordx2 v[34:35], v[2:3], off offset:96
	v_mul_f32_e32 v2, v14, v36
	v_mul_f32_e32 v3, v15, v36
	v_cvt_pk_bf16_f32 v2, v2, v3
	v_mul_f32_e32 v3, v16, v36
	v_mul_f32_e32 v4, v17, v36
	v_cvt_pk_bf16_f32 v3, v3, v4
	global_store_dwordx2 v[34:35], v[2:3], off offset:112
	s_cbranch_scc0 .LBB0_821
